# grid barrier: one early L2 write-back issued by the arriver four places before the last of its XCC, so the last arriver's release fence finds fewer dirty lines
# speedup vs baseline: 1.0224x; 1.0186x over previous
; DEV unsigned xb_ld(unsigned* p) { return __hip_atomic_load(p, __ATOMIC_RELAXED, __HIP_MEMORY_SCOPE_AGENT); }
; DEV unsigned xb_add(unsigned* p, unsigned v) { return __hip_atomic_fetch_add(p, v, __ATOMIC_RELAXED, __HIP_MEMORY_SCOPE_AGENT); }
; #define XB_SPIN(cond, bar) do { unsigned _sp = 0; while (cond) { __builtin_amdgcn_s_sleep(1); \
;     if ((++_sp & 255u) == 0u) { if (xb_ld(&(bar)[XB_TMO])) break; if (_sp > XB_SPIN_CAP) { atomicAdd(&(bar)[XB_TMO], 1u); break; } } } } while (0)
; DEV void xcd_barrier(const XcdBarrier& b) {
;     ...
;         const unsigned old = xb_add(&bar[XB_XSUB(b.x)], 1u);
;         const unsigned gen = old / nloc;
;         if (old + 1u == (gen + 1u) * nloc) {
;             __builtin_amdgcn_fence(__ATOMIC_RELEASE, "agent");
;             asm volatile("s_waitcnt vmcnt(0)" ::: "memory");
;             const unsigned og = xb_add(&bar[XB_TOP], 1u);
;             const unsigned tg = og / nx;
;             if (og + 1u == (tg + 1u) * nx) xb_add(&bar[XB_TOPGEN], 1u);
;             else XB_SPIN(xb_ld(&bar[XB_TOPGEN]) == tg, bar);
;             __builtin_amdgcn_fence(__ATOMIC_ACQUIRE, "agent");
;             xb_add(&bar[XB_XGEN(b.x)], 1u);
;             asm volatile("s_waitcnt vmcnt(0)" ::: "memory");
.LBB0_134:
	s_lshl_b32 s6, s3, 8
	v_mov_b32_e32 v2, 0x20008
	s_add_u32 s6, s28, s6
	s_addc_u32 s7, s29, 0
	ds_read_b32 v2, v2
	v_mov_b32_e32 v4, 0x1000
	v_mov_b32_e32 v5, 1
	global_atomic_add v4, v4, v5, s[6:7] offset:1024 sc0
	s_waitcnt vmcnt(0) lgkmcnt(0)
	buffer_inv sc1
	v_readfirstlane_b32 s8, v4
	v_readfirstlane_b32 s9, v3
	v_readfirstlane_b32 s10, v2
	v_readfirstlane_b32 s11, v1
	s_add_i32 s12, s10, 1
	v_mov_b32_e32 v6, 0x20008
	v_mov_b32_e32 v5, s12
	ds_write_b32 v6, v5
	s_add_i32 s8, s8, 1
	s_mul_i32 s13, s12, s9
	s_sub_i32 s16, s13, 4
	s_cmp_lg_u32 s8, s16
	s_cbranch_scc1 .Lxb0_nopre
	buffer_wbl2 sc1
.Lxb0_nopre:
	s_cmp_lg_u32 s8, s13
	s_cbranch_scc1 .Lxb0_poll
	buffer_wbl2 sc1
	s_waitcnt vmcnt(0)
	v_mov_b32_e32 v4, 0x3000
	v_mov_b32_e32 v5, 1
	global_atomic_add v4, v4, v5, s[28:29] offset:1024 sc0
	s_waitcnt vmcnt(0)
	v_readfirstlane_b32 s8, v4
	s_mul_i32 s13, s12, s11
	s_add_i32 s8, s8, 1
	s_cmp_lg_u32 s8, s13
	s_cbranch_scc1 .Lxb0_poll
	v_mov_b32_e32 v4, 0x2000
	v_mov_b32_e32 v6, 0x3000
	global_atomic_add v4, v5, s[28:29] offset:1024
	global_atomic_add v4, v5, s[28:29] offset:1280
	global_atomic_add v4, v5, s[28:29] offset:1536
	global_atomic_add v4, v5, s[28:29] offset:1792
	global_atomic_add v4, v5, s[28:29] offset:2048
	global_atomic_add v4, v5, s[28:29] offset:2304
	global_atomic_add v4, v5, s[28:29] offset:2560
	global_atomic_add v4, v5, s[28:29] offset:2816
	global_atomic_add v4, v5, s[28:29] offset:3072
	global_atomic_add v4, v5, s[28:29] offset:3328
	global_atomic_add v4, v5, s[28:29] offset:3584
	global_atomic_add v4, v5, s[28:29] offset:3840
	global_atomic_add v6, v5, s[28:29] offset:0
	global_atomic_add v6, v5, s[28:29] offset:256
	global_atomic_add v6, v5, s[28:29] offset:512
	global_atomic_add v6, v5, s[28:29] offset:768
	s_branch .Lxb0_done
